# speedup vs baseline: 1.1621x; 1.0058x over previous
.LBB0_169:
	v_max_u32_dpp v103, v99, v99 quad_perm:[1,0,3,2] row_mask:0xf bank_mask:0xf
	s_nop 1
	v_max_u32_dpp v103, v103, v103 quad_perm:[2,3,0,1] row_mask:0xf bank_mask:0xf
	s_nop 1
	v_max_u32_dpp v103, v103, v103 row_half_mirror row_mask:0xf bank_mask:0xf
	s_nop 1
	v_max_u32_dpp v103, v103, v103 row_mirror row_mask:0xf bank_mask:0xf
	v_cmp_eq_u32_e32 vcc, v99, v103
	s_nop 1
	v_cndmask_b32_e32 v99, v99, v101, vcc
	v_cndmask_b32_e32 v101, v101, v102, vcc
	v_cndmask_b32_e32 v102, v102, v100, vcc
	v_cndmask_b32_e64 v100, v100, 0, vcc
	v_cmp_eq_u32_e32 vcc, s0, v83
	s_add_i32 s0, s0, 1
	s_cmp_lg_u32 s0, 16
	v_cndmask_b32_e32 v98, v98, v103, vcc
	s_cbranch_scc1 .LBB0_169
	s_setprio 3
	v_not_b32_e32 v99, v98
	v_lshrrev_b32_e32 v99, 4, v99
	v_and_or_b32 v99, v99, 15, v156
	v_lshlrev_b32_e32 v99, 2, v99
	v_cmp_lt_i32_e32 vcc, -1, v98
	ds_bpermute_b32 v96, v99, v96
	s_movk_i32 s0, 0xff00
	v_cndmask_b32_e64 v99, v189, -1, vcc
	v_bitop3_b32 v99, v99, v98, s0 bitop3:0x78
	ds_bpermute_b32 v100, v157, v99
	v_bitop3_b32 v98, v98, v156, 15 bitop3:0xce
	v_lshlrev_b32_e32 v98, 2, v98
	ds_bpermute_b32 v97, v98, v97
	s_waitcnt lgkmcnt(2)
	v_lshlrev_b32_e32 v96, 7, v96
	s_waitcnt lgkmcnt(1)
	v_sub_f32_e32 v98, v99, v100
	v_mul_f32_e32 v98, 0x3fb8aa3b, v98
	v_exp_f32_e32 v112, v98
	v_and_b32_e32 v96, 0x3f80, v96
	s_waitcnt lgkmcnt(0)
	v_and_b32_e32 v97, 0x7f, v97
	v_bitop3_b32 v113, v97, s74, v96 bitop3:0x36
	v_add_f32_dpp v96, v112, v112 quad_perm:[1,0,3,2] row_mask:0xf bank_mask:0xf bound_ctrl:1
	v_readlane_b32 s0, v254, 52
	s_waitcnt vmcnt(18)
	v_lshlrev_b32_e32 v120, 16, v46
	v_add_f32_dpp v96, v96, v96 quad_perm:[2,3,0,1] row_mask:0xf bank_mask:0xf bound_ctrl:1
	v_add_u32_e32 v226, s0, v94
	v_and_b32_e32 v121, 0xffff0000, v46
	v_add_f32_dpp v96, v96, v96 row_half_mirror row_mask:0xf bank_mask:0xf bound_ctrl:1
	v_lshlrev_b32_e32 v46, 16, v47
	v_and_b32_e32 v47, 0xffff0000, v47
	v_add_f32_dpp v114, v96, v96 row_mirror row_mask:0xf bank_mask:0xf bound_ctrl:1
	v_min_i32_e32 v96, 0x3fff, v226
	v_ashrrev_i32_e32 v97, 31, v96
	v_lshlrev_b64 v[96:97], 12, v[96:97]
	v_lshl_add_u64 v[96:97], v[92:93], 0, v[96:97]
	global_load_dwordx2 v[110:111], v[96:97], off
	global_load_dwordx2 v[108:109], v[96:97], off offset:512
	global_load_dwordx2 v[106:107], v[96:97], off offset:1024
	global_load_dwordx2 v[104:105], v[96:97], off offset:1536
	global_load_dwordx2 v[102:103], v[96:97], off offset:2048
	global_load_dwordx2 v[100:101], v[96:97], off offset:2560
	global_load_dwordx2 v[98:99], v[96:97], off offset:3072
	s_nop 0
	global_load_dwordx2 v[96:97], v[96:97], off offset:3584
	v_div_scale_f32 v115, s[6:7], v114, v114, v112
	v_rcp_f32_e32 v116, v115
	v_lshlrev_b32_e32 v122, 16, v48
	v_and_b32_e32 v123, 0xffff0000, v48
	v_lshlrev_b32_e32 v48, 16, v49
	v_fma_f32 v117, -v115, v116, 1.0
	v_fmac_f32_e32 v116, v117, v116
	v_div_scale_f32 v117, vcc, v112, v114, v112
	v_mul_f32_e32 v118, v117, v116
	v_fma_f32 v119, -v115, v118, v117
	v_fmac_f32_e32 v118, v119, v116
	v_fma_f32 v115, -v115, v118, v117
	v_div_fmas_f32 v115, v115, v116, v118
	v_div_fixup_f32 v112, v115, v114, v112
	ds_write2st64_b32 v154, v112, v113 offset0:137 offset1:139
	s_waitcnt vmcnt(24)
	v_lshlrev_b32_e32 v112, 16, v54
	v_and_b32_e32 v113, 0xffff0000, v54
	v_lshlrev_b32_e32 v54, 16, v55
	v_and_b32_e32 v55, 0xffff0000, v55
	v_lshlrev_b32_e32 v114, 16, v56
	v_and_b32_e32 v115, 0xffff0000, v56
	v_lshlrev_b32_e32 v56, 16, v57
	v_and_b32_e32 v57, 0xffff0000, v57
	v_lshlrev_b32_e32 v116, 16, v50
	v_and_b32_e32 v117, 0xffff0000, v50
	v_lshlrev_b32_e32 v50, 16, v51
	v_and_b32_e32 v51, 0xffff0000, v51
	v_lshlrev_b32_e32 v118, 16, v52
	v_and_b32_e32 v119, 0xffff0000, v52
	v_lshlrev_b32_e32 v52, 16, v53
	v_and_b32_e32 v53, 0xffff0000, v53
	v_and_b32_e32 v49, 0xffff0000, v49
	v_lshlrev_b32_e32 v126, 16, v38
	v_and_b32_e32 v127, 0xffff0000, v38
	v_lshlrev_b32_e32 v38, 16, v39
	v_and_b32_e32 v39, 0xffff0000, v39
	v_lshlrev_b32_e32 v128, 16, v40
	v_and_b32_e32 v129, 0xffff0000, v40
	v_lshlrev_b32_e32 v40, 16, v41
	v_and_b32_e32 v41, 0xffff0000, v41
	s_waitcnt vmcnt(20)
	v_lshlrev_b32_e32 v130, 16, v42
	v_and_b32_e32 v131, 0xffff0000, v42
	v_lshlrev_b32_e32 v42, 16, v43
	v_and_b32_e32 v43, 0xffff0000, v43
	v_lshlrev_b32_e32 v132, 16, v44
	v_and_b32_e32 v133, 0xffff0000, v44
	v_lshlrev_b32_e32 v44, 16, v45
	v_and_b32_e32 v45, 0xffff0000, v45
	v_lshlrev_b32_e32 v134, 16, v34
	v_and_b32_e32 v135, 0xffff0000, v34
	v_lshlrev_b32_e32 v34, 16, v35
	v_and_b32_e32 v35, 0xffff0000, v35
	v_lshlrev_b32_e32 v136, 16, v36
	v_and_b32_e32 v137, 0xffff0000, v36
	v_lshlrev_b32_e32 v36, 16, v37
	v_and_b32_e32 v37, 0xffff0000, v37
	v_lshlrev_b32_e32 v138, 16, v30
	v_and_b32_e32 v139, 0xffff0000, v30
	v_lshlrev_b32_e32 v140, 16, v31
	v_and_b32_e32 v141, 0xffff0000, v31
	v_lshlrev_b32_e32 v142, 16, v32
	v_and_b32_e32 v143, 0xffff0000, v32
	v_lshlrev_b32_e32 v144, 16, v33
	v_and_b32_e32 v145, 0xffff0000, v33
	v_lshlrev_b32_e32 v146, 16, v26
	v_and_b32_e32 v147, 0xffff0000, v26
	v_lshlrev_b32_e32 v148, 16, v27
	v_and_b32_e32 v149, 0xffff0000, v27
	v_lshlrev_b32_e32 v150, 16, v28
	v_and_b32_e32 v151, 0xffff0000, v28
	v_lshlrev_b32_e32 v152, 16, v29
	v_and_b32_e32 v153, 0xffff0000, v29
	s_setprio 3
	ds_read_b32 v240, v217 offset:35376
	v_lshlrev_b32_e32 v245, 2, v124
	v_add_u32_e32 v245, 0xb800, v245
	v_add_u32_e32 v227, 0x8a00, v217
	s_movk_i32 s0, 0x200
	s_mov_b32 s2, 0
	v_cndmask_b32_e64 v244, v245, v221, s[44:45]
	s_waitcnt lgkmcnt(0)
	ds_read_b32 v241, v227 offset:64
	s_waitcnt vmcnt(5)
	v_mad_u64_u32 v[242:243], s[6:7], v240, s0, v[84:85]
	global_load_dwordx4 v[30:33], v[242:243], off
	global_load_dwordx4 v[26:29], v[242:243], off offset:256
	v_cvt_scalef32_pk_f32_fp4 v[196:197], v66, 1.0
	v_cvt_scalef32_pk_f32_fp4 v[198:199], v66, 1.0 op_sel:[1,0,0]
	v_cvt_scalef32_pk_f32_fp4 v[230:231], v66, 1.0 op_sel:[0,1,0]
	v_cvt_scalef32_pk_f32_fp4 v[232:233], v66, 1.0 op_sel:[1,1,0]
	v_pk_fma_f32 v[234:235], v[112:113], v[196:197], 0 op_sel_hi:[1,1,0]
	v_pk_fma_f32 v[236:237], v[54:55], v[198:199], 0 op_sel_hi:[1,1,0]
	v_pk_fma_f32 v[234:235], v[114:115], v[230:231], v[234:235]
	v_pk_fma_f32 v[236:237], v[56:57], v[232:233], v[236:237]
	v_cvt_scalef32_pk_f32_fp4 v[196:197], v67, 1.0
	v_cvt_scalef32_pk_f32_fp4 v[198:199], v67, 1.0 op_sel:[1,0,0]
	v_cvt_scalef32_pk_f32_fp4 v[230:231], v67, 1.0 op_sel:[0,1,0]
	v_cvt_scalef32_pk_f32_fp4 v[232:233], v67, 1.0 op_sel:[1,1,0]
	v_pk_fma_f32 v[234:235], v[116:117], v[196:197], v[234:235]
	v_pk_fma_f32 v[236:237], v[50:51], v[198:199], v[236:237]
	v_pk_fma_f32 v[234:235], v[118:119], v[230:231], v[234:235]
	v_pk_fma_f32 v[236:237], v[52:53], v[232:233], v[236:237]
	v_cvt_scalef32_pk_f32_fp4 v[196:197], v68, 1.0
	v_cvt_scalef32_pk_f32_fp4 v[198:199], v68, 1.0 op_sel:[1,0,0]
	v_cvt_scalef32_pk_f32_fp4 v[230:231], v68, 1.0 op_sel:[0,1,0]
	v_cvt_scalef32_pk_f32_fp4 v[232:233], v68, 1.0 op_sel:[1,1,0]
	v_pk_fma_f32 v[234:235], v[120:121], v[196:197], v[234:235]
	v_pk_fma_f32 v[236:237], v[46:47], v[198:199], v[236:237]
	v_pk_fma_f32 v[234:235], v[122:123], v[230:231], v[234:235]
	v_pk_fma_f32 v[236:237], v[48:49], v[232:233], v[236:237]
	v_cvt_scalef32_pk_f32_fp4 v[196:197], v69, 1.0
	v_cvt_scalef32_pk_f32_fp4 v[198:199], v69, 1.0 op_sel:[1,0,0]
	v_cvt_scalef32_pk_f32_fp4 v[230:231], v69, 1.0 op_sel:[0,1,0]
	v_cvt_scalef32_pk_f32_fp4 v[232:233], v69, 1.0 op_sel:[1,1,0]
	v_pk_fma_f32 v[234:235], v[126:127], v[196:197], v[234:235]
	v_pk_fma_f32 v[236:237], v[38:39], v[198:199], v[236:237]
	v_pk_fma_f32 v[234:235], v[128:129], v[230:231], v[234:235]
	v_pk_fma_f32 v[236:237], v[40:41], v[232:233], v[236:237]
	s_waitcnt vmcnt(6)
	v_cvt_scalef32_pk_f32_fp4 v[196:197], v58, 1.0
	v_cvt_scalef32_pk_f32_fp4 v[198:199], v58, 1.0 op_sel:[1,0,0]
	v_cvt_scalef32_pk_f32_fp4 v[230:231], v58, 1.0 op_sel:[0,1,0]
	v_cvt_scalef32_pk_f32_fp4 v[232:233], v58, 1.0 op_sel:[1,1,0]
	v_pk_fma_f32 v[234:235], v[130:131], v[196:197], v[234:235]
	v_pk_fma_f32 v[236:237], v[42:43], v[198:199], v[236:237]
	v_pk_fma_f32 v[234:235], v[132:133], v[230:231], v[234:235]
	v_pk_fma_f32 v[236:237], v[44:45], v[232:233], v[236:237]
	v_cvt_scalef32_pk_f32_fp4 v[196:197], v59, 1.0
	v_cvt_scalef32_pk_f32_fp4 v[198:199], v59, 1.0 op_sel:[1,0,0]
	v_cvt_scalef32_pk_f32_fp4 v[230:231], v59, 1.0 op_sel:[0,1,0]
	v_cvt_scalef32_pk_f32_fp4 v[232:233], v59, 1.0 op_sel:[1,1,0]
	v_pk_fma_f32 v[234:235], v[134:135], v[196:197], v[234:235]
	v_pk_fma_f32 v[236:237], v[34:35], v[198:199], v[236:237]
	v_pk_fma_f32 v[234:235], v[136:137], v[230:231], v[234:235]
	v_pk_fma_f32 v[236:237], v[36:37], v[232:233], v[236:237]
	v_cvt_scalef32_pk_f32_fp4 v[196:197], v60, 1.0
	v_cvt_scalef32_pk_f32_fp4 v[198:199], v60, 1.0 op_sel:[1,0,0]
	v_cvt_scalef32_pk_f32_fp4 v[230:231], v60, 1.0 op_sel:[0,1,0]
	v_cvt_scalef32_pk_f32_fp4 v[232:233], v60, 1.0 op_sel:[1,1,0]
	v_pk_fma_f32 v[234:235], v[138:139], v[196:197], v[234:235]
	v_pk_fma_f32 v[236:237], v[140:141], v[198:199], v[236:237]
	v_pk_fma_f32 v[234:235], v[142:143], v[230:231], v[234:235]
	v_pk_fma_f32 v[236:237], v[144:145], v[232:233], v[236:237]
	v_cvt_scalef32_pk_f32_fp4 v[196:197], v61, 1.0
	v_cvt_scalef32_pk_f32_fp4 v[198:199], v61, 1.0 op_sel:[1,0,0]
	v_cvt_scalef32_pk_f32_fp4 v[230:231], v61, 1.0 op_sel:[0,1,0]
	v_cvt_scalef32_pk_f32_fp4 v[232:233], v61, 1.0 op_sel:[1,1,0]
	v_pk_fma_f32 v[234:235], v[146:147], v[196:197], v[234:235]
	v_pk_fma_f32 v[236:237], v[148:149], v[198:199], v[236:237]
	v_pk_fma_f32 v[234:235], v[150:151], v[230:231], v[234:235]
	v_pk_fma_f32 v[236:237], v[152:153], v[232:233], v[236:237]
	v_add_f32_e32 v238, v236, v237
	v_add_f32_e32 v242, v234, v235
	v_add_f32_e32 v238, v242, v238
	s_waitcnt lgkmcnt(0)
	s_nop 0
	v_add_f32_dpp v238, v238, v238 quad_perm:[1,0,3,2] row_mask:0xf bank_mask:0xf bound_ctrl:1
	ds_read_b32 v240, v227 offset:80
	s_waitcnt vmcnt(5)
	v_add_f32_dpp v238, v238, v238 quad_perm:[2,3,0,1] row_mask:0xf bank_mask:0xf bound_ctrl:1
	v_mad_u64_u32 v[242:243], s[6:7], v241, s0, v[84:85]
	global_load_dwordx4 v[66:69], v[242:243], off
	v_add_f32_dpp v238, v238, v238 row_half_mirror row_mask:0xf bank_mask:0xf bound_ctrl:1
	global_load_dwordx4 v[58:61], v[242:243], off offset:256
	s_nop 0
	v_add_f32_dpp v238, v238, v238 row_mirror row_mask:0xf bank_mask:0xf bound_ctrl:1
	ds_write_b32 v244, v238 offset:0

.LBB0_723:
	s_setprio 3
	s_waitcnt lgkmcnt(0)
	s_barrier
	s_and_saveexec_b64 s[6:7], s[46:47]
	s_cbranch_execz .LBB0_726
	s_lshl_b32 s0, s20, 2
	s_and_b32 s2, s0, 0x3e000
	v_lshl_add_u64 v[2:3], v[114:115], 0, s[2:3]
	s_mov_b64 s[10:11], 0
	v_mov_b32_e32 v4, v141
	v_mov_b32_e32 v5, v140
